# v013 plus non-temporal hint on the MLP-up epilogue stores (the 285 MB hidden activation is written once and read once, larger than the last-level cache)
# speedup vs baseline: 1.0065x; 1.0065x over previous
; __device__ __forceinline__ unsigned pk2e(float lo, float hi) { typedef float v2f __attribute__((ext_vector_type(2))); typedef __bf16 v2b __attribute__((ext_vector_type(2))); v2f v = {lo, hi}; v2b b = __builtin_convertvector(v, v2b); return __builtin_bit_cast(unsigned, b); }
;     __device__ __forceinline__ void operator()(const f32x4 (&acc)[2][2][4][2], const Unit& u, int wr, int wc, int fr_, int fq_) const {
;         int ln_ = threadIdx.x & 63; asm volatile("" : "+v"(ln_)); const int fr = ln_ & 15, fq = ln_ >> 4; (void)fr_; (void)fq_;
;         const int row0 = u.pm * BM + wr * 64 + fr; int colt = u.pn * BM; bf16_t* base = O0; int ld = ld0;
;         if (split_col && colt >= split_col) { base = O1; ld = ld1; colt -= split_col; }
;         const int col0 = colt + wc * 32 + 8 * fq;
; #pragma unroll
;         for (int ai = 0; ai < 2; ++ai)
; #pragma unroll
;             for (int m = 0; m < 4; ++m) { bf16_t* rowp = base + (size_t)(row0 + ai * HALF + m * 16) * ld + col0;
; #pragma unroll
;                 for (int bj = 0; bj < 2; ++bj) { f32x4 v0 = acc[ai][bj][m][0], v1 = acc[ai][bj][m][1];
;                     if (act) {
; #pragma unroll
;                         for (int e = 0; e < 4; ++e) { float a = v0[e] > 0.f ? v0[e] : 0.f; v0[e] = a * a; float b = v1[e] > 0.f ? v1[e] : 0.f; v1[e] = b * b; } }
;                     u32x4 w; w.x = pk2e(v0[0], v0[1]); w.y = pk2e(v0[2], v0[3]); w.z = pk2e(v1[0], v1[1]); w.w = pk2e(v1[2], v1[3]);
;                     *(u32x4*)(rowp + bj * HALF) = w; } }
.LBB0_1236:
	v_max_f32_e32 v123, v123, v123
	v_max_f32_e32 v122, v122, v122
	v_max_f32_e32 v123, 0, v123
	v_max_f32_e32 v122, 0, v122
	v_mov_b32_e32 v140, v220
	s_lshl_b32 s27, s40, 8
	v_pk_mul_f32 v[148:149], v[122:123], v[122:123]
	v_max_f32_e32 v122, v129, v129
	s_add_i32 s27, s27, s41
	v_max_f32_e32 v123, 0, v122
	v_max_f32_e32 v122, v128, v128
	v_and_or_b32 v144, v140, 15, s27
	s_lshl_b32 s27, s55, 8
	v_ashrrev_i32_e32 v140, 1, v140
	v_max_f32_e32 v122, 0, v122
	v_and_b32_e32 v140, -8, v140
	s_or_b32 s27, s27, s44
	v_pk_mul_f32 v[128:129], v[122:123], v[122:123]
	v_max_f32_e32 v122, v125, v125
	v_add_u32_e32 v140, s27, v140
	v_max_f32_e32 v127, v127, v127
	v_max_f32_e32 v126, v126, v126
	v_max_f32_e32 v123, 0, v122
	v_max_f32_e32 v122, v124, v124
	v_ashrrev_i32_e32 v141, 31, v140
	v_ashrrev_i32_e32 v145, 31, v144
	v_max_f32_e32 v127, 0, v127
	v_max_f32_e32 v126, 0, v126
	v_max_f32_e32 v122, 0, v122
	v_lshl_add_u64 v[146:147], v[140:141], 1, s[8:9]
	v_lshlrev_b64 v[140:141], 13, v[144:145]
	v_pk_mul_f32 v[126:127], v[126:127], v[126:127]
	v_pk_mul_f32 v[150:151], v[122:123], v[122:123]
	v_max_f32_e32 v115, v115, v115
	v_max_f32_e32 v114, v114, v114
	v_lshl_add_u64 v[140:141], v[146:147], 0, v[140:141]
	v_cvt_pk_bf16_f32 v122, v126, v127
	v_cvt_pk_bf16_f32 v123, v128, v129
	v_cvt_pk_bf16_f32 v124, v148, v149
	v_cvt_pk_bf16_f32 v125, v150, v151
	v_max_f32_e32 v115, 0, v115
	v_max_f32_e32 v114, 0, v114
	global_store_dwordx4 v[140:141], v[122:125], off nt
	v_max_f32_e32 v119, v119, v119
	v_max_f32_e32 v118, v118, v118
	v_pk_mul_f32 v[122:123], v[114:115], v[114:115]
	v_max_f32_e32 v114, v121, v121
	v_max_f32_e32 v115, 0, v114
	v_max_f32_e32 v114, v120, v120
	v_max_f32_e32 v114, 0, v114
	v_pk_mul_f32 v[120:121], v[114:115], v[114:115]
	v_max_f32_e32 v114, v117, v117
	v_max_f32_e32 v115, 0, v114
	v_max_f32_e32 v114, v116, v116
	v_max_f32_e32 v119, 0, v119
	v_max_f32_e32 v118, 0, v118
	v_max_f32_e32 v114, 0, v114
	v_pk_mul_f32 v[118:119], v[118:119], v[118:119]
	v_pk_mul_f32 v[124:125], v[114:115], v[114:115]
	v_max_f32_e32 v105, v105, v105
	v_max_f32_e32 v104, v104, v104
	v_cvt_pk_bf16_f32 v114, v118, v119
	v_cvt_pk_bf16_f32 v115, v120, v121
	v_cvt_pk_bf16_f32 v116, v122, v123
	v_cvt_pk_bf16_f32 v117, v124, v125
	v_max_f32_e32 v105, 0, v105
	v_max_f32_e32 v104, 0, v104
	global_store_dwordx4 v[140:141], v[114:117], off offset:256 nt
	v_max_f32_e32 v109, v109, v109
	v_max_f32_e32 v108, v108, v108
	v_pk_mul_f32 v[116:117], v[104:105], v[104:105]
	v_max_f32_e32 v104, v111, v111
	v_max_f32_e32 v105, 0, v104
	v_max_f32_e32 v104, v110, v110
	v_max_f32_e32 v104, 0, v104
	v_pk_mul_f32 v[110:111], v[104:105], v[104:105]
	v_max_f32_e32 v104, v107, v107
	v_or_b32_e32 v114, 16, v144
	v_max_f32_e32 v105, 0, v104
	v_max_f32_e32 v104, v106, v106
	v_ashrrev_i32_e32 v115, 31, v114
	v_max_f32_e32 v109, 0, v109
	v_max_f32_e32 v108, 0, v108
	v_max_f32_e32 v104, 0, v104
	v_lshlrev_b64 v[114:115], 13, v[114:115]
	v_pk_mul_f32 v[108:109], v[108:109], v[108:109]
	v_pk_mul_f32 v[118:119], v[104:105], v[104:105]
	v_max_f32_e32 v97, v97, v97
	v_max_f32_e32 v96, v96, v96
	v_lshl_add_u64 v[114:115], v[146:147], 0, v[114:115]
	v_cvt_pk_bf16_f32 v104, v108, v109
	v_cvt_pk_bf16_f32 v105, v110, v111
	v_cvt_pk_bf16_f32 v106, v116, v117
	v_cvt_pk_bf16_f32 v107, v118, v119
	v_max_f32_e32 v97, 0, v97
	v_max_f32_e32 v96, 0, v96
	global_store_dwordx4 v[114:115], v[104:107], off nt
	v_max_f32_e32 v101, v101, v101
	v_max_f32_e32 v100, v100, v100
	v_pk_mul_f32 v[104:105], v[96:97], v[96:97]
	v_max_f32_e32 v96, v103, v103
	v_max_f32_e32 v97, 0, v96
	v_max_f32_e32 v96, v102, v102
	v_max_f32_e32 v96, 0, v96
	v_pk_mul_f32 v[102:103], v[96:97], v[96:97]
	v_max_f32_e32 v96, v99, v99
	v_max_f32_e32 v97, 0, v96
	v_max_f32_e32 v96, v98, v98
	v_max_f32_e32 v101, 0, v101
	v_max_f32_e32 v100, 0, v100
	v_max_f32_e32 v96, 0, v96
	v_pk_mul_f32 v[100:101], v[100:101], v[100:101]
	v_pk_mul_f32 v[106:107], v[96:97], v[96:97]
	v_max_f32_e32 v89, v89, v89
	v_max_f32_e32 v88, v88, v88
	v_cvt_pk_bf16_f32 v96, v100, v101
	v_cvt_pk_bf16_f32 v97, v102, v103
	v_cvt_pk_bf16_f32 v98, v104, v105
	v_cvt_pk_bf16_f32 v99, v106, v107
	v_max_f32_e32 v89, 0, v89
	v_max_f32_e32 v88, 0, v88
	global_store_dwordx4 v[114:115], v[96:99], off offset:256 nt
	v_max_f32_e32 v93, v93, v93
	v_max_f32_e32 v92, v92, v92
	v_pk_mul_f32 v[98:99], v[88:89], v[88:89]
	v_max_f32_e32 v88, v95, v95
	v_max_f32_e32 v89, 0, v88
	v_max_f32_e32 v88, v94, v94
	v_max_f32_e32 v88, 0, v88
	v_pk_mul_f32 v[94:95], v[88:89], v[88:89]
	v_max_f32_e32 v88, v91, v91
	v_or_b32_e32 v96, 32, v144
	v_max_f32_e32 v89, 0, v88
	v_max_f32_e32 v88, v90, v90
	v_ashrrev_i32_e32 v97, 31, v96
	v_max_f32_e32 v93, 0, v93
	v_max_f32_e32 v92, 0, v92
	v_max_f32_e32 v88, 0, v88
	v_lshlrev_b64 v[96:97], 13, v[96:97]
	v_pk_mul_f32 v[92:93], v[92:93], v[92:93]
	v_pk_mul_f32 v[100:101], v[88:89], v[88:89]
	v_max_f32_e32 v81, v81, v81
	v_max_f32_e32 v80, v80, v80
	v_lshl_add_u64 v[96:97], v[146:147], 0, v[96:97]
	v_cvt_pk_bf16_f32 v88, v92, v93
	v_cvt_pk_bf16_f32 v89, v94, v95
	v_cvt_pk_bf16_f32 v90, v98, v99
	v_cvt_pk_bf16_f32 v91, v100, v101
	v_max_f32_e32 v81, 0, v81
	v_max_f32_e32 v80, 0, v80
	global_store_dwordx4 v[96:97], v[88:91], off nt
	v_max_f32_e32 v85, v85, v85
	v_max_f32_e32 v84, v84, v84
	v_pk_mul_f32 v[88:89], v[80:81], v[80:81]
	v_max_f32_e32 v80, v87, v87
	v_max_f32_e32 v81, 0, v80
	v_max_f32_e32 v80, v86, v86
	v_max_f32_e32 v80, 0, v80
	v_pk_mul_f32 v[86:87], v[80:81], v[80:81]
	v_max_f32_e32 v80, v83, v83
	v_max_f32_e32 v81, 0, v80
	v_max_f32_e32 v80, v82, v82
	v_max_f32_e32 v85, 0, v85
	v_max_f32_e32 v84, 0, v84
	v_max_f32_e32 v80, 0, v80
; __device__ __forceinline__ unsigned pk2e(float lo, float hi) { typedef float v2f __attribute__((ext_vector_type(2))); typedef __bf16 v2b __attribute__((ext_vector_type(2))); v2f v = {lo, hi}; v2b b = __builtin_convertvector(v, v2b); return __builtin_bit_cast(unsigned, b); }
;     __device__ __forceinline__ void operator()(const f32x4 (&acc)[2][2][4][2], const Unit& u, int wr, int wc, int fr_, int fq_) const {
;     ...
;             for (int m = 0; m < 4; ++m) { bf16_t* rowp = base + (size_t)(row0 + ai * HALF + m * 16) * ld + col0;
; #pragma unroll
;                 for (int bj = 0; bj < 2; ++bj) { f32x4 v0 = acc[ai][bj][m][0], v1 = acc[ai][bj][m][1];
;                     if (act) {
; #pragma unroll
;                         for (int e = 0; e < 4; ++e) { float a = v0[e] > 0.f ? v0[e] : 0.f; v0[e] = a * a; float b = v1[e] > 0.f ? v1[e] : 0.f; v1[e] = b * b; } }
;                     u32x4 w; w.x = pk2e(v0[0], v0[1]); w.y = pk2e(v0[2], v0[3]); w.z = pk2e(v1[0], v1[1]); w.w = pk2e(v1[2], v1[3]);
;                     *(u32x4*)(rowp + bj * HALF) = w; } }
	v_pk_mul_f32 v[84:85], v[84:85], v[84:85]
	v_pk_mul_f32 v[90:91], v[80:81], v[80:81]
	v_max_f32_e32 v73, v73, v73
	v_max_f32_e32 v72, v72, v72
	v_cvt_pk_bf16_f32 v80, v84, v85
	v_cvt_pk_bf16_f32 v81, v86, v87
	v_cvt_pk_bf16_f32 v82, v88, v89
	v_cvt_pk_bf16_f32 v83, v90, v91
	v_max_f32_e32 v73, 0, v73
	v_max_f32_e32 v72, 0, v72
	global_store_dwordx4 v[96:97], v[80:83], off offset:256 nt
	v_max_f32_e32 v77, v77, v77
	v_max_f32_e32 v76, v76, v76
	v_pk_mul_f32 v[82:83], v[72:73], v[72:73]
	v_max_f32_e32 v72, v79, v79
	v_max_f32_e32 v73, 0, v72
	v_max_f32_e32 v72, v78, v78
	v_max_f32_e32 v72, 0, v72
	v_pk_mul_f32 v[78:79], v[72:73], v[72:73]
	v_max_f32_e32 v72, v75, v75
	v_or_b32_e32 v80, 48, v144
	v_max_f32_e32 v73, 0, v72
	v_max_f32_e32 v72, v74, v74
	v_ashrrev_i32_e32 v81, 31, v80
	v_max_f32_e32 v77, 0, v77
	v_max_f32_e32 v76, 0, v76
	v_max_f32_e32 v72, 0, v72
	v_lshlrev_b64 v[80:81], 13, v[80:81]
	v_pk_mul_f32 v[76:77], v[76:77], v[76:77]
	v_pk_mul_f32 v[84:85], v[72:73], v[72:73]
	v_max_f32_e32 v65, v65, v65
	v_max_f32_e32 v64, v64, v64
	v_lshl_add_u64 v[80:81], v[146:147], 0, v[80:81]
	v_cvt_pk_bf16_f32 v72, v76, v77
	v_cvt_pk_bf16_f32 v73, v78, v79
	v_cvt_pk_bf16_f32 v74, v82, v83
	v_cvt_pk_bf16_f32 v75, v84, v85
	v_max_f32_e32 v65, 0, v65
	v_max_f32_e32 v64, 0, v64
	global_store_dwordx4 v[80:81], v[72:75], off nt
	v_max_f32_e32 v69, v69, v69
	v_max_f32_e32 v68, v68, v68
	v_pk_mul_f32 v[72:73], v[64:65], v[64:65]
	v_max_f32_e32 v64, v71, v71
	v_max_f32_e32 v65, 0, v64
	v_max_f32_e32 v64, v70, v70
	v_max_f32_e32 v64, 0, v64
	v_pk_mul_f32 v[70:71], v[64:65], v[64:65]
	v_max_f32_e32 v64, v67, v67
	v_max_f32_e32 v65, 0, v64
	v_max_f32_e32 v64, v66, v66
	v_max_f32_e32 v69, 0, v69
	v_max_f32_e32 v68, 0, v68
	v_max_f32_e32 v64, 0, v64
	v_pk_mul_f32 v[68:69], v[68:69], v[68:69]
	v_pk_mul_f32 v[74:75], v[64:65], v[64:65]
	v_max_f32_e32 v57, v57, v57
	v_max_f32_e32 v56, v56, v56
	v_cvt_pk_bf16_f32 v64, v68, v69
	v_cvt_pk_bf16_f32 v65, v70, v71
	v_cvt_pk_bf16_f32 v66, v72, v73
	v_cvt_pk_bf16_f32 v67, v74, v75
	v_max_f32_e32 v57, 0, v57
	v_max_f32_e32 v56, 0, v56
	global_store_dwordx4 v[80:81], v[64:67], off offset:256 nt
	v_max_f32_e32 v61, v61, v61
	v_max_f32_e32 v60, v60, v60
	v_pk_mul_f32 v[66:67], v[56:57], v[56:57]
	v_max_f32_e32 v56, v63, v63
	v_max_f32_e32 v57, 0, v56
	v_max_f32_e32 v56, v62, v62
	v_max_f32_e32 v56, 0, v56
	v_pk_mul_f32 v[62:63], v[56:57], v[56:57]
	v_max_f32_e32 v56, v59, v59
	v_max_f32_e32 v61, 0, v61
	v_max_f32_e32 v60, 0, v60
	v_max_f32_e32 v57, 0, v56
	v_max_f32_e32 v56, v58, v58
	v_pk_mul_f32 v[60:61], v[60:61], v[60:61]
	v_max_f32_e32 v56, 0, v56
	s_mov_b32 s27, 0x100000
	v_pk_mul_f32 v[68:69], v[56:57], v[56:57]
	v_cvt_pk_bf16_f32 v56, v60, v61
	v_add_co_u32_e32 v60, vcc, s27, v140
	v_max_f32_e32 v49, v49, v49
	v_max_f32_e32 v48, v48, v48
	v_cvt_pk_bf16_f32 v57, v62, v63
	v_cvt_pk_bf16_f32 v58, v66, v67
	v_cvt_pk_bf16_f32 v59, v68, v69
	v_addc_co_u32_e32 v61, vcc, 0, v141, vcc
	v_max_f32_e32 v49, 0, v49
	v_max_f32_e32 v48, 0, v48
	global_store_dwordx4 v[60:61], v[56:59], off nt
	v_max_f32_e32 v53, v53, v53
	v_max_f32_e32 v52, v52, v52
	v_pk_mul_f32 v[56:57], v[48:49], v[48:49]
	v_max_f32_e32 v48, v55, v55
	v_max_f32_e32 v49, 0, v48
	v_max_f32_e32 v48, v54, v54
	v_max_f32_e32 v48, 0, v48
	v_pk_mul_f32 v[54:55], v[48:49], v[48:49]
	v_max_f32_e32 v48, v51, v51
	v_max_f32_e32 v49, 0, v48
	v_max_f32_e32 v48, v50, v50
	v_max_f32_e32 v53, 0, v53
	v_max_f32_e32 v52, 0, v52
	v_max_f32_e32 v48, 0, v48
	s_mov_b64 s[42:43], 0x100000
	v_pk_mul_f32 v[52:53], v[52:53], v[52:53]
	v_pk_mul_f32 v[58:59], v[48:49], v[48:49]
	v_max_f32_e32 v41, v41, v41
	v_max_f32_e32 v40, v40, v40
	v_lshl_add_u64 v[64:65], v[140:141], 0, s[42:43]
	v_cvt_pk_bf16_f32 v48, v52, v53
	v_cvt_pk_bf16_f32 v49, v54, v55
	v_cvt_pk_bf16_f32 v50, v56, v57
	v_cvt_pk_bf16_f32 v51, v58, v59
	v_max_f32_e32 v41, 0, v41
	v_max_f32_e32 v40, 0, v40
	global_store_dwordx4 v[64:65], v[48:51], off offset:256 nt
	v_max_f32_e32 v45, v45, v45
	v_max_f32_e32 v44, v44, v44
	v_pk_mul_f32 v[50:51], v[40:41], v[40:41]
	v_max_f32_e32 v40, v47, v47
	v_max_f32_e32 v41, 0, v40
	v_max_f32_e32 v40, v46, v46
	v_max_f32_e32 v40, 0, v40
	v_pk_mul_f32 v[46:47], v[40:41], v[40:41]
	v_max_f32_e32 v40, v43, v43
	v_max_f32_e32 v45, 0, v45
	v_max_f32_e32 v44, 0, v44
	v_max_f32_e32 v41, 0, v40
	v_max_f32_e32 v40, v42, v42
	v_pk_mul_f32 v[44:45], v[44:45], v[44:45]
	v_max_f32_e32 v40, 0, v40
	s_mov_b32 s27, 0x120000
	v_pk_mul_f32 v[52:53], v[40:41], v[40:41]
	v_cvt_pk_bf16_f32 v40, v44, v45
	v_add_co_u32_e32 v44, vcc, s27, v140
	v_max_f32_e32 v33, v33, v33
	v_max_f32_e32 v32, v32, v32
	v_cvt_pk_bf16_f32 v41, v46, v47
; __device__ __forceinline__ unsigned pk2e(float lo, float hi) { typedef float v2f __attribute__((ext_vector_type(2))); typedef __bf16 v2b __attribute__((ext_vector_type(2))); v2f v = {lo, hi}; v2b b = __builtin_convertvector(v, v2b); return __builtin_bit_cast(unsigned, b); }
; #define PG8_BAR __builtin_amdgcn_s_barrier()
;     __device__ __forceinline__ void operator()(const f32x4 (&acc)[2][2][4][2], const Unit& u, int wr, int wc, int fr_, int fq_) const {
;     ...
;             for (int m = 0; m < 4; ++m) { bf16_t* rowp = base + (size_t)(row0 + ai * HALF + m * 16) * ld + col0;
; #pragma unroll
;                 for (int bj = 0; bj < 2; ++bj) { f32x4 v0 = acc[ai][bj][m][0], v1 = acc[ai][bj][m][1];
;                     if (act) {
; #pragma unroll
;                         for (int e = 0; e < 4; ++e) { float a = v0[e] > 0.f ? v0[e] : 0.f; v0[e] = a * a; float b = v1[e] > 0.f ? v1[e] : 0.f; v1[e] = b * b; } }
;                     u32x4 w; w.x = pk2e(v0[0], v0[1]); w.y = pk2e(v0[2], v0[3]); w.z = pk2e(v1[0], v1[1]); w.w = pk2e(v1[2], v1[3]);
;                     *(u32x4*)(rowp + bj * HALF) = w; } }
; template <class Epi, class Sched, bool ALIGN_EPI = false, bool SP2 = false>
; __device__ __forceinline__ void gemm_phase(PG8_LAS unsigned char* lds, const Gemm g, const Sched& S, const Epi& E) {
;     ...
;         if constexpr (!Epi::AFTER_DRAIN) { E(acc, cur, wr, wc, fr, fq); S.done(cur); }
;         if (!has_next) break;
; #pragma unroll
;         for (int a = 0; a < 2; ++a)
; #pragma unroll
;             for (int b = 0; b < 2; ++b)
; #pragma unroll
;                 for (int m = 0; m < 4; ++m)
; #pragma unroll
;                     for (int n = 0; n < 2; ++n) acc[a][b][m][n] = (f32x4){0.f, 0.f, 0.f, 0.f};
;         cur = nxt; cA = nA; cB = nB; ++ui;
;         if constexpr (ALIGN_EPI) { if (wr == 1) PG8_BAR; }
	v_cvt_pk_bf16_f32 v42, v50, v51
	v_cvt_pk_bf16_f32 v43, v52, v53
	v_addc_co_u32_e32 v45, vcc, 0, v141, vcc
	v_max_f32_e32 v33, 0, v33
	v_max_f32_e32 v32, 0, v32
	global_store_dwordx4 v[44:45], v[40:43], off nt
	v_max_f32_e32 v37, v37, v37
	v_max_f32_e32 v36, v36, v36
	v_pk_mul_f32 v[40:41], v[32:33], v[32:33]
	v_max_f32_e32 v32, v39, v39
	v_max_f32_e32 v33, 0, v32
	v_max_f32_e32 v32, v38, v38
	v_max_f32_e32 v32, 0, v32
	v_pk_mul_f32 v[38:39], v[32:33], v[32:33]
	v_max_f32_e32 v32, v35, v35
	v_max_f32_e32 v33, 0, v32
	v_max_f32_e32 v32, v34, v34
	v_max_f32_e32 v37, 0, v37
	v_max_f32_e32 v36, 0, v36
	v_max_f32_e32 v32, 0, v32
	s_mov_b64 s[42:43], 0x120000
	v_pk_mul_f32 v[36:37], v[36:37], v[36:37]
	v_pk_mul_f32 v[42:43], v[32:33], v[32:33]
	v_max_f32_e32 v25, v25, v25
	v_max_f32_e32 v24, v24, v24
	v_lshl_add_u64 v[48:49], v[140:141], 0, s[42:43]
	v_cvt_pk_bf16_f32 v32, v36, v37
	v_cvt_pk_bf16_f32 v33, v38, v39
	v_cvt_pk_bf16_f32 v34, v40, v41
	v_cvt_pk_bf16_f32 v35, v42, v43
	v_max_f32_e32 v25, 0, v25
	v_max_f32_e32 v24, 0, v24
	global_store_dwordx4 v[48:49], v[32:35], off offset:256 nt
	v_max_f32_e32 v29, v29, v29
	v_max_f32_e32 v28, v28, v28
	v_pk_mul_f32 v[34:35], v[24:25], v[24:25]
	v_max_f32_e32 v24, v31, v31
	v_max_f32_e32 v25, 0, v24
	v_max_f32_e32 v24, v30, v30
	v_max_f32_e32 v24, 0, v24
	v_pk_mul_f32 v[30:31], v[24:25], v[24:25]
	v_max_f32_e32 v24, v27, v27
	v_max_f32_e32 v29, 0, v29
	v_max_f32_e32 v28, 0, v28
	v_max_f32_e32 v25, 0, v24
	v_max_f32_e32 v24, v26, v26
	v_pk_mul_f32 v[28:29], v[28:29], v[28:29]
	v_max_f32_e32 v24, 0, v24
	s_mov_b32 s27, 0x140000
	v_pk_mul_f32 v[36:37], v[24:25], v[24:25]
	v_cvt_pk_bf16_f32 v24, v28, v29
	v_add_co_u32_e32 v28, vcc, s27, v140
	v_max_f32_e32 v17, v17, v17
	v_max_f32_e32 v16, v16, v16
	v_cvt_pk_bf16_f32 v25, v30, v31
	v_cvt_pk_bf16_f32 v26, v34, v35
	v_cvt_pk_bf16_f32 v27, v36, v37
	v_addc_co_u32_e32 v29, vcc, 0, v141, vcc
	v_max_f32_e32 v17, 0, v17
	v_max_f32_e32 v16, 0, v16
	global_store_dwordx4 v[28:29], v[24:27], off nt
	v_max_f32_e32 v21, v21, v21
	v_max_f32_e32 v20, v20, v20
	v_pk_mul_f32 v[24:25], v[16:17], v[16:17]
	v_max_f32_e32 v16, v23, v23
	v_max_f32_e32 v17, 0, v16
	v_max_f32_e32 v16, v22, v22
	v_max_f32_e32 v16, 0, v16
	v_pk_mul_f32 v[22:23], v[16:17], v[16:17]
	v_max_f32_e32 v16, v19, v19
	v_max_f32_e32 v17, 0, v16
	v_max_f32_e32 v16, v18, v18
	v_max_f32_e32 v21, 0, v21
	v_max_f32_e32 v20, 0, v20
	v_max_f32_e32 v16, 0, v16
	s_mov_b64 s[42:43], 0x140000
	v_pk_mul_f32 v[20:21], v[20:21], v[20:21]
	v_pk_mul_f32 v[26:27], v[16:17], v[16:17]
	v_max_f32_e32 v9, v9, v9
	v_max_f32_e32 v8, v8, v8
	v_lshl_add_u64 v[32:33], v[140:141], 0, s[42:43]
	v_cvt_pk_bf16_f32 v16, v20, v21
	v_cvt_pk_bf16_f32 v17, v22, v23
	v_cvt_pk_bf16_f32 v18, v24, v25
	v_cvt_pk_bf16_f32 v19, v26, v27
	v_max_f32_e32 v9, 0, v9
	v_max_f32_e32 v8, 0, v8
	global_store_dwordx4 v[32:33], v[16:19], off offset:256 nt
	v_max_f32_e32 v13, v13, v13
	v_max_f32_e32 v12, v12, v12
	v_pk_mul_f32 v[18:19], v[8:9], v[8:9]
	v_max_f32_e32 v8, v15, v15
	v_max_f32_e32 v9, 0, v8
	v_max_f32_e32 v8, v14, v14
	v_max_f32_e32 v8, 0, v8
	v_pk_mul_f32 v[14:15], v[8:9], v[8:9]
	v_max_f32_e32 v8, v11, v11
	v_max_f32_e32 v13, 0, v13
	v_max_f32_e32 v12, 0, v12
	v_max_f32_e32 v9, 0, v8
	v_max_f32_e32 v8, v10, v10
	v_pk_mul_f32 v[12:13], v[12:13], v[12:13]
	v_max_f32_e32 v8, 0, v8
	s_mov_b32 s27, 0x160000
	v_pk_mul_f32 v[20:21], v[8:9], v[8:9]
	v_cvt_pk_bf16_f32 v8, v12, v13
	v_add_co_u32_e32 v12, vcc, s27, v140
	v_max_f32_e32 v1, v1, v1
	v_max_f32_e32 v0, v0, v0
	v_cvt_pk_bf16_f32 v9, v14, v15
	v_cvt_pk_bf16_f32 v10, v18, v19
	v_cvt_pk_bf16_f32 v11, v20, v21
	v_addc_co_u32_e32 v13, vcc, 0, v141, vcc
	v_max_f32_e32 v1, 0, v1
	v_max_f32_e32 v0, 0, v0
	global_store_dwordx4 v[12:13], v[8:11], off nt
	v_max_f32_e32 v5, v5, v5
	v_max_f32_e32 v4, v4, v4
	v_pk_mul_f32 v[8:9], v[0:1], v[0:1]
	v_max_f32_e32 v0, v7, v7
	v_max_f32_e32 v1, 0, v0
	v_max_f32_e32 v0, v6, v6
	v_max_f32_e32 v0, 0, v0
	v_pk_mul_f32 v[6:7], v[0:1], v[0:1]
	v_max_f32_e32 v0, v3, v3
	v_max_f32_e32 v1, 0, v0
	v_max_f32_e32 v0, v2, v2
	v_max_f32_e32 v5, 0, v5
	v_max_f32_e32 v4, 0, v4
	v_max_f32_e32 v0, 0, v0
	s_mov_b64 s[42:43], 0x160000
	v_pk_mul_f32 v[4:5], v[4:5], v[4:5]
	v_pk_mul_f32 v[10:11], v[0:1], v[0:1]
	v_lshl_add_u64 v[16:17], v[140:141], 0, s[42:43]
	v_cvt_pk_bf16_f32 v0, v4, v5
	v_cvt_pk_bf16_f32 v1, v6, v7
	v_cvt_pk_bf16_f32 v2, v8, v9
	v_cvt_pk_bf16_f32 v3, v10, v11
	s_andn2_b64 vcc, exec, s[12:13]
	s_mov_b64 s[12:13], -1
	global_store_dwordx4 v[16:17], v[0:3], off offset:256 nt
	s_cbranch_vccnz .LBB0_1229
	s_andn2_b64 vcc, exec, s[6:7]
	s_cbranch_vccnz .LBB0_1228
	s_barrier
	s_branch .LBB0_1228
